# plus: K-norm row loop no longer waits for its row stores' acks at the loop top (drain moved before the loop)
# speedup vs baseline: 1.0069x; 1.0022x over previous
; DI int ltid(int wv) { int l; asm volatile("v_mbcnt_lo_u32_b32 %0, -1, 0\n\tv_mbcnt_hi_u32_b32 %0, -1, %0" : "=v"(l)); return wv * 64 + l; }
; DI void phase_qknorm(const Params& p, int j, int wv) {
;   const int tid = ltid(wv); const int lane = tid & 63, w = tid >> 6;
;   const int tsel = lane >> 5, hh = (lane >> 1) & 15, axis = lane & 1;
;   const int qk = 1;
;   u16* QKB = (u16*)(p.ws + R_QKB);
;   const float* gam = p.in[qk ? 25 : 24] + j * 64 + axis * 32;
;   float gm[32];
; #pragma unroll
;   for (int d = 0; d < 32; ++d) gm[d] = gam[d];
;   const float qscale = qk ? 1.f : 0.125f * 1.4426950408889634f;
;   const int rstride = gridDim.x * 16;
;   const int lcol = qk * 1024 + hh * 64 + axis * 32;
;   uint4 nu[4];
;   {
;     const int row0 = (blockIdx.x * 8 + w) * 2 + tsel;
;     if (row0 < NT) {
; #pragma unroll
;       for (int q = 0; q < 4; ++q) nu[q] = *(const uint4*)(QKB + (size_t)row0 * 2048 + lcol + q * 8);
;     }
;   }
;   for (int row = (blockIdx.x * 8 + w) * 2 + tsel; row < NT; row += rstride) {
;     u16* ptr = QKB + (size_t)row * 2048 + lcol;
;     float v[32]; float ss = 0.f;
;     uint4 cu[4];
; #pragma unroll
;     for (int q = 0; q < 4; ++q) cu[q] = nu[q];
;     if (row + rstride < NT) {
; #pragma unroll
;       for (int q = 0; q < 4; ++q) nu[q] = *(const uint4*)(QKB + (size_t)(row + rstride) * 2048 + lcol + q * 8);
;     }
.LBB0_411:
	s_or_b64 exec, exec, s[4:5]
	v_readlane_b32 s0, v252, 60
	v_readlane_b32 s1, v252, 61
	s_andn2_b64 vcc, exec, s[0:1]
	s_waitcnt lgkmcnt(0)
	s_barrier
	s_cbranch_vccnz .LBB0_420
	v_mbcnt_lo_u32_b32 v36, -1, 0
	v_mbcnt_hi_u32_b32 v36, -1, v36
	v_readlane_b32 s0, v254, 53
	v_add_u32_e32 v0, s53, v36
	v_ashrrev_i32_e32 v0, 5, v0
	v_and_b32_e32 v35, -2, v0
	v_bfe_u32 v34, v36, 5, 1
	v_add_u32_e32 v0, s0, v35
	v_or_b32_e32 v72, v0, v34
	v_cmp_gt_i32_e32 vcc, s16, v72
	s_and_saveexec_b64 s[8:9], vcc
	s_cbranch_execz .LBB0_419
	v_readlane_b32 s0, v255, 0
	v_readlane_b32 s1, v255, 1
	s_mov_b32 s5, s1
	v_readlane_b32 s0, v255, 41
	v_readlane_b32 s1, v255, 42
	s_lshl_b32 s4, s0, 6
	v_readlane_b32 s20, v251, 0
	s_mov_b32 s1, s5
	s_lshl_b64 s[4:5], s[4:5], 2
	v_readlane_b32 s22, v251, 2
	v_and_b32_e32 v37, 1, v36
	v_readlane_b32 s23, v251, 3
	s_add_u32 s4, s22, s4
	s_addc_u32 s5, s23, s5
	v_lshlrev_b32_e32 v0, 7, v37
	global_load_dwordx4 v[2:5], v0, s[4:5] offset:48
	global_load_dwordx4 v[6:9], v0, s[4:5] offset:32
	global_load_dwordx4 v[10:13], v0, s[4:5] offset:16
	global_load_dwordx4 v[14:17], v0, s[4:5]
	global_load_dwordx4 v[18:21], v0, s[4:5] offset:112
	global_load_dwordx4 v[22:25], v0, s[4:5] offset:96
	global_load_dwordx4 v[26:29], v0, s[4:5] offset:80
	global_load_dwordx4 v[30:33], v0, s[4:5] offset:64
	v_ashrrev_i32_e32 v73, 31, v72
	v_lshlrev_b32_e32 v0, 6, v36
	v_lshlrev_b64 v[38:39], 12, v[72:73]
	v_and_b32_e32 v0, 0x780, v0
	v_lshl_add_u64 v[40:41], s[92:93], 0, v[38:39]
	v_lshl_or_b32 v0, v37, 6, v0
	v_lshl_add_u64 v[40:41], v[40:41], 0, v[0:1]
	global_load_dwordx4 v[50:53], v[40:41], off offset:2096
	global_load_dwordx4 v[54:57], v[40:41], off offset:2080
	global_load_dwordx4 v[58:61], v[40:41], off offset:2064
	global_load_dwordx4 v[62:65], v[40:41], off offset:2048
	v_writelane_b32 v255, s0, 0
	v_readlane_b32 s21, v251, 1
	v_and_b32_e32 v36, 63, v36
	v_writelane_b32 v255, s1, 1
	v_readlane_b32 s0, v254, 54
	v_readlane_b32 s20, v255, 23
	v_lshlrev_b32_e32 v36, 2, v36
	v_add3_u32 v34, s0, v34, v35
	v_ashrrev_i32_e32 v35, 31, v34
	v_lshlrev_b64 v[34:35], 12, v[34:35]
	v_readlane_b32 s22, v255, 25
	v_readlane_b32 s23, v255, 26
	v_cmp_eq_u32_e64 s[4:5], 0, v37
	v_xor_b32_e32 v92, 4, v36
	v_lshl_add_u64 v[66:67], s[22:23], 0, v[38:39]
	v_or_b32_e32 v0, 0x800, v0
	v_lshl_add_u64 v[68:69], s[22:23], 0, v[34:35]
	s_mov_b64 s[12:13], 0
	v_readlane_b32 s24, v251, 4
	v_readlane_b32 s25, v251, 5
	v_readlane_b32 s26, v251, 6
	v_readlane_b32 s27, v251, 7
	v_readlane_b32 s21, v255, 24
	s_waitcnt vmcnt(11)
	v_mov_b32_e32 v70, v5
	s_waitcnt vmcnt(7)
	v_mov_b32_e32 v71, v21
	s_waitcnt vmcnt(0)
	s_branch .LBB0_415

; DI void phase_qknorm(const Params& p, int j, int wv) {
;     ...
;   for (int row = (blockIdx.x * 8 + w) * 2 + tsel; row < NT; row += rstride) {
;     u16* ptr = QKB + (size_t)row * 2048 + lcol;
;     float v[32]; float ss = 0.f;
;     uint4 cu[4];
; #pragma unroll
;     for (int q = 0; q < 4; ++q) cu[q] = nu[q];
;     if (row + rstride < NT) {
; #pragma unroll
;       for (int q = 0; q < 4; ++q) nu[q] = *(const uint4*)(QKB + (size_t)(row + rstride) * 2048 + lcol + q * 8);
;     }
.LBB0_415:
	v_readlane_b32 s0, v254, 55
	s_nop 0
	v_mov_b64_e32 v[34:35], v[62:63]
	v_mov_b64_e32 v[36:37], v[64:65]
	v_add_u32_e32 v5, s0, v72
	s_mov_b32 s0, 0x11fff
	v_cmp_gt_i32_e32 vcc, s16, v5
	v_cmp_lt_i32_e64 s[6:7], s0, v5
	v_mov_b64_e32 v[46:47], v[58:59]
	v_mov_b64_e32 v[48:49], v[60:61]
	v_mov_b64_e32 v[42:43], v[54:55]
	v_mov_b64_e32 v[44:45], v[56:57]
	v_mov_b64_e32 v[38:39], v[50:51]
	v_mov_b64_e32 v[40:41], v[52:53]
	v_readlane_b32 s1, v254, 56
	s_and_saveexec_b64 s[18:19], vcc
	s_cbranch_execz .LBB0_417
	v_lshl_add_u64 v[34:35], v[68:69], 0, v[0:1]
	s_mov_b64 s[0:1], 0x12000000
	v_lshl_add_u64 v[46:47], v[34:35], 0, s[0:1]
	v_add_co_u32_e32 v34, vcc, 0x12000000, v34
	s_nop 1
	v_addc_co_u32_e32 v35, vcc, 0, v35, vcc
	global_load_dwordx4 v[34:37], v[34:35], off
	s_nop 0
	global_load_dwordx4 v[38:41], v[46:47], off offset:48
	global_load_dwordx4 v[42:45], v[46:47], off offset:32
	s_nop 0
	global_load_dwordx4 v[46:49], v[46:47], off offset:16

; DI int ltid(int wv) { int l; asm volatile("v_mbcnt_lo_u32_b32 %0, -1, 0\n\tv_mbcnt_hi_u32_b32 %0, -1, %0" : "=v"(l)); return wv * 64 + l; }
; DI void phase_qknorm(const Params& p, int j, int wv) {
;   const int tid = ltid(wv); const int lane = tid & 63, w = tid >> 6;
;   const int tsel = lane >> 5, hh = (lane >> 1) & 15, axis = lane & 1;
;   const int qk = 1;
;   u16* QKB = (u16*)(p.ws + R_QKB);
;   const float* gam = p.in[qk ? 25 : 24] + j * 64 + axis * 32;
;   float gm[32];
; #pragma unroll
;   for (int d = 0; d < 32; ++d) gm[d] = gam[d];
;   const float qscale = qk ? 1.f : 0.125f * 1.4426950408889634f;
;   const int rstride = gridDim.x * 16;
;   const int lcol = qk * 1024 + hh * 64 + axis * 32;
;   uint4 nu[4];
;   {
;     const int row0 = (blockIdx.x * 8 + w) * 2 + tsel;
;     if (row0 < NT) {
; #pragma unroll
;       for (int q = 0; q < 4; ++q) nu[q] = *(const uint4*)(QKB + (size_t)row0 * 2048 + lcol + q * 8);
;     }
;   }
;   for (int row = (blockIdx.x * 8 + w) * 2 + tsel; row < NT; row += rstride) {
;     u16* ptr = QKB + (size_t)row * 2048 + lcol;
;     float v[32]; float ss = 0.f;
;     uint4 cu[4];
; #pragma unroll
;     for (int q = 0; q < 4; ++q) cu[q] = nu[q];
;     if (row + rstride < NT) {
; #pragma unroll
;       for (int q = 0; q < 4; ++q) nu[q] = *(const uint4*)(QKB + (size_t)(row + rstride) * 2048 + lcol + q * 8);
;     }
.LBB0_458:
	v_readlane_b32 s0, v252, 58
	v_readlane_b32 s1, v252, 59
	s_andn2_b64 vcc, exec, s[0:1]
	s_cbranch_vccnz .LBB0_467
	s_waitcnt lgkmcnt(0)
	s_barrier
	v_mbcnt_lo_u32_b32 v36, -1, 0
	v_mbcnt_hi_u32_b32 v36, -1, v36
	v_readlane_b32 s0, v254, 53
	v_add_u32_e32 v0, s53, v36
	v_ashrrev_i32_e32 v0, 5, v0
	v_and_b32_e32 v35, -2, v0
	v_bfe_u32 v34, v36, 5, 1
	v_add_u32_e32 v0, s0, v35
	v_or_b32_e32 v72, v0, v34
	v_cmp_gt_i32_e32 vcc, s16, v72
	s_and_saveexec_b64 s[8:9], vcc
	s_cbranch_execz .LBB0_466
	v_readlane_b32 s0, v255, 0
	v_readlane_b32 s1, v255, 1
	s_mov_b32 s5, s1
	v_readlane_b32 s0, v255, 41
	v_readlane_b32 s1, v255, 42
	s_lshl_b32 s4, s0, 6
	v_readlane_b32 s16, v251, 0
	s_mov_b32 s1, s5
	s_lshl_b64 s[4:5], s[4:5], 2
	v_readlane_b32 s18, v251, 2
	v_and_b32_e32 v37, 1, v36
	v_readlane_b32 s19, v251, 3
	s_add_u32 s4, s18, s4
	s_addc_u32 s5, s19, s5
	v_lshlrev_b32_e32 v0, 7, v37
	global_load_dwordx4 v[2:5], v0, s[4:5] offset:48
	global_load_dwordx4 v[6:9], v0, s[4:5] offset:32
	global_load_dwordx4 v[10:13], v0, s[4:5] offset:16
	global_load_dwordx4 v[14:17], v0, s[4:5]
	global_load_dwordx4 v[18:21], v0, s[4:5] offset:112
	global_load_dwordx4 v[22:25], v0, s[4:5] offset:96
	global_load_dwordx4 v[26:29], v0, s[4:5] offset:80
	global_load_dwordx4 v[30:33], v0, s[4:5] offset:64
	v_ashrrev_i32_e32 v73, 31, v72
	v_lshlrev_b32_e32 v0, 6, v36
	v_lshlrev_b64 v[38:39], 12, v[72:73]
	v_and_b32_e32 v0, 0x780, v0
	v_lshl_add_u64 v[40:41], s[92:93], 0, v[38:39]
	v_lshl_or_b32 v0, v37, 6, v0
	v_lshl_add_u64 v[40:41], v[40:41], 0, v[0:1]
	global_load_dwordx4 v[50:53], v[40:41], off offset:2096
	global_load_dwordx4 v[54:57], v[40:41], off offset:2080
	global_load_dwordx4 v[58:61], v[40:41], off offset:2064
	global_load_dwordx4 v[62:65], v[40:41], off offset:2048
	v_writelane_b32 v255, s0, 0
	v_readlane_b32 s17, v251, 1
	v_and_b32_e32 v36, 63, v36
	v_writelane_b32 v255, s1, 1
	v_readlane_b32 s0, v254, 54
	v_readlane_b32 s16, v255, 23
	v_lshlrev_b32_e32 v36, 2, v36
	v_add3_u32 v34, s0, v34, v35
	v_ashrrev_i32_e32 v35, 31, v34
	v_lshlrev_b64 v[34:35], 12, v[34:35]
	v_readlane_b32 s18, v255, 25
	v_readlane_b32 s19, v255, 26
	s_mov_b32 s10, 0x12000
	v_cmp_eq_u32_e64 s[4:5], 0, v37
	v_xor_b32_e32 v92, 4, v36
	v_lshl_add_u64 v[66:67], s[18:19], 0, v[38:39]
	v_or_b32_e32 v0, 0x800, v0
	v_lshl_add_u64 v[68:69], s[18:19], 0, v[34:35]
	s_mov_b64 s[12:13], 0
	v_readlane_b32 s20, v251, 4
	v_readlane_b32 s21, v251, 5
	v_readlane_b32 s22, v251, 6
	v_readlane_b32 s23, v251, 7
	v_readlane_b32 s17, v255, 24
	s_waitcnt vmcnt(11)
	v_mov_b32_e32 v70, v5
	s_waitcnt vmcnt(7)
	v_mov_b32_e32 v71, v21
	s_waitcnt vmcnt(0)
	s_branch .LBB0_462

; DI void phase_qknorm(const Params& p, int j, int wv) {
;     ...
;   for (int row = (blockIdx.x * 8 + w) * 2 + tsel; row < NT; row += rstride) {
;     u16* ptr = QKB + (size_t)row * 2048 + lcol;
;     float v[32]; float ss = 0.f;
;     uint4 cu[4];
; #pragma unroll
;     for (int q = 0; q < 4; ++q) cu[q] = nu[q];
;     if (row + rstride < NT) {
; #pragma unroll
;       for (int q = 0; q < 4; ++q) nu[q] = *(const uint4*)(QKB + (size_t)(row + rstride) * 2048 + lcol + q * 8);
;     }
.LBB0_462:
	v_readlane_b32 s0, v254, 55
	s_nop 0
	v_mov_b64_e32 v[34:35], v[62:63]
	v_mov_b64_e32 v[36:37], v[64:65]
	v_add_u32_e32 v5, s0, v72
	s_mov_b32 s0, 0x11fff
	v_cmp_gt_i32_e32 vcc, s10, v5
	v_cmp_lt_i32_e64 s[6:7], s0, v5
	v_mov_b64_e32 v[46:47], v[58:59]
	v_mov_b64_e32 v[48:49], v[60:61]
	v_mov_b64_e32 v[42:43], v[54:55]
	v_mov_b64_e32 v[44:45], v[56:57]
	v_mov_b64_e32 v[38:39], v[50:51]
	v_mov_b64_e32 v[40:41], v[52:53]
	v_readlane_b32 s1, v254, 56
	s_and_saveexec_b64 s[18:19], vcc
	s_cbranch_execz .LBB0_464
	v_lshl_add_u64 v[34:35], v[68:69], 0, v[0:1]
	s_mov_b64 s[0:1], 0x12000000
	v_lshl_add_u64 v[46:47], v[34:35], 0, s[0:1]
	v_add_co_u32_e32 v34, vcc, 0x12000000, v34
	s_nop 1
	v_addc_co_u32_e32 v35, vcc, 0, v35, vcc
	global_load_dwordx4 v[34:37], v[34:35], off
	s_nop 0
	global_load_dwordx4 v[38:41], v[46:47], off offset:48
	global_load_dwordx4 v[42:45], v[46:47], off offset:32
	s_nop 0
	global_load_dwordx4 v[46:49], v[46:47], off offset:16
